# final RMSNorm made class-local (class c normalises batch c right after its own last down-GEMM; the flat grid barrier before it is gone)
# speedup vs baseline: 1.0005x; 1.0005x over previous
; #define PHASE_IDS() const int tid = opaque_tid(), lane = tid & 63, r16 = lane & 15, q4 = lane >> 4; (void)r16; (void)q4; (void)tid
; DI float rstd4(f32x4 p) { return rsqrtf(((p.x + p.y) + (p.z + p.w)) * (1.f / DM) + EPS); }
; __global__ void __launch_bounds__(512, 2) fwd_megakernel(Args args) {
;     ...
;     for (int m0 = gw; m0 < MTOK; m0 += 4 * NGW) {
;         PHASE_IDS();
;         u32x4 xv[4][2]; f32x4 pv4[4];
; #pragma unroll
;         for (int r = 0; r < 4; ++r) { const int m = min(m0 + r * NGW, MTOK - 1);
;             const u32x4* xr = (const u32x4*)(xb + (size_t)m * DM) + lane; xv[r][0] = xr[0]; xv[r][1] = xr[64];
;             pv4[r] = *(const f32x4*)(ssq + (size_t)6 * MTOK * 4 + (size_t)m * 4); }
;         const f32x4* wv = (const f32x4*)args.in[26];
;         f32x4 wq[2][2];
; #pragma unroll
;         for (int j = 0; j < 2; ++j) { const int c4 = (64 * j + lane) * 2; wq[j][0] = wv[c4]; wq[j][1] = wv[c4 + 1]; }
; #pragma unroll
;         for (int r = 0; r < 4; ++r) { const int m = m0 + r * NGW; if (m < MTOK) {
;             const float rs = rstd4(pv4[r]); f32x4* orow = (f32x4*)(args.out + (size_t)m * DM);
; #pragma unroll
;             for (int j = 0; j < 2; ++j) {
;                 float v[8]; unpack8(xv[r][j], v);
;                 const int c4 = (64 * j + lane) * 2; const f32x4 w0 = wq[j][0], w1 = wq[j][1];
;                 orow[c4] = (f32x4){v[0] * rs * w0.x, v[1] * rs * w0.y, v[2] * rs * w0.z, v[3] * rs * w0.w};
;                 orow[c4 + 1] = (f32x4){v[4] * rs * w1.x, v[5] * rs * w1.y, v[6] * rs * w1.z, v[7] * rs * w1.w};
;             } } }
.LBB0_1285:
	v_readlane_b32 s0, v251, 0
	s_and_b32 s1, s0, 7
	s_lshr_b32 s0, s0, 3
	s_lshl_b32 s0, s0, 3
	v_readlane_b32 s2, v252, 0
	s_add_i32 s0, s0, s2
	s_lshl_b32 s1, s1, 12
	s_add_i32 s52, s0, s1
	s_add_i32 s32, s1, 0xfff
	s_movk_i32 s51, 0x100
	s_movk_i32 s75, 0x200
	s_movk_i32 s55, 0x300
	s_movk_i32 s74, 0x400
	v_readlane_b32 s0, v253, 40
	v_readlane_b32 s1, v253, 41
	s_andn2_b64 vcc, exec, s[0:1]
	s_cbranch_vccnz .LBB0_1294
	s_add_u32 s8, s80, 0x5c00000
	s_addc_u32 s9, s81, 0
	v_mov_b32_e32 v53, 0
	v_mov_b32_e32 v54, 0x358637bd
	s_mov_b32 s10, 0x800000
	s_branch .LBB0_1288
.LBB0_1287:
	s_add_i32 s52, s52, s74
	s_cmp_gt_i32 s52, s32
	s_cbranch_scc1 .LBB0_1294
